# gla_m2: gla_norm loads issued with gate rows (L0); v-row loads hoisted to job top (both layers)
# baseline (speedup 1.0000x reference)
.LBB0_643:
	v_lshrrev_b32_e32 v1, 4, v171
	v_lshlrev_b32_e32 v7, 1, v120
	v_mul_lo_u32 v1, v1, s85
	v_and_b32_e32 v7, 0x78, v7
	v_add3_u32 v1, 0, v1, v7
	s_waitcnt lgkmcnt(0)
	s_barrier
	s_waitcnt vmcnt(6)
	v_cvt_pk_bf16_f32 v2, v132, v133
	s_waitcnt vmcnt(4)
	v_cvt_pk_bf16_f32 v3, v134, v135
	s_waitcnt vmcnt(2)
	v_cvt_pk_bf16_f32 v4, v128, v129
	s_waitcnt vmcnt(0)
	v_cvt_pk_bf16_f32 v5, v130, v131
	ds_write2_b64 v1, v[2:3], v[4:5] offset1:16
	v_lshrrev_b32_e32 v1, 4, v172
	v_mul_lo_u32 v1, v1, s85
	v_add3_u32 v1, 0, v1, v7
	v_cvt_pk_bf16_f32 v2, v140, v141
	v_cvt_pk_bf16_f32 v3, v142, v143
	v_cvt_pk_bf16_f32 v4, v136, v137
	v_cvt_pk_bf16_f32 v5, v138, v139
	ds_write2_b64 v1, v[2:3], v[4:5] offset1:16
	v_lshrrev_b32_e32 v1, 4, v173
	v_mul_lo_u32 v1, v1, s85
	v_add3_u32 v1, 0, v1, v7
	v_cvt_pk_bf16_f32 v2, v148, v149
	v_cvt_pk_bf16_f32 v3, v150, v151
	v_cvt_pk_bf16_f32 v4, v144, v145
	v_cvt_pk_bf16_f32 v5, v146, v147
	ds_write2_b64 v1, v[2:3], v[4:5] offset1:16
	v_lshrrev_b32_e32 v1, 4, v174
	v_mul_lo_u32 v1, v1, s85
	v_ashrrev_i32_e32 v30, 6, v171
	v_add3_u32 v1, 0, v1, v7
	v_cvt_pk_bf16_f32 v2, v156, v157
	v_cvt_pk_bf16_f32 v3, v158, v159
	v_cvt_pk_bf16_f32 v4, v152, v153
	v_cvt_pk_bf16_f32 v5, v154, v155
	ds_write2_b64 v1, v[2:3], v[4:5] offset1:16
	v_lshlrev_b32_e32 v1, 5, v30
	v_and_b32_e32 v31, 32, v1
	v_bfi_b32 v1, -16, v170, v171
	v_and_b32_e32 v0, 15, v171
	v_mul_lo_u32 v2, v1, s87
	v_and_b32_e32 v32, 48, v171
	v_add3_u32 v33, s86, v2, v32
	v_add3_u32 v35, s89, v2, v32
	v_add_u32_e32 v38, 0, v2
	v_or_b32_e32 v2, v31, v0
	v_mul_u32_u24_e32 v2, 0x48, v2
	v_add_u32_e32 v34, s88, v32
	v_lshlrev_b32_e32 v18, 1, v2
	v_bfe_u32 v6, v171, 4, 2
	v_add_u32_e32 v36, s52, v32
	v_add_u32_e32 v14, v34, v18
	v_lshlrev_b32_e32 v37, 2, v6
	v_lshlrev_b32_e32 v39, 3, v6
	ds_read_b128 v[2:5], v33
	ds_read_b128 v[6:9], v14
	ds_read_b128 v[10:13], v33 offset:64
	ds_read_b128 v[14:17], v14 offset:64
	v_add_u32_e32 v26, v36, v18
	ds_read_b128 v[18:21], v35
	ds_read_b128 v[22:25], v26
	s_waitcnt lgkmcnt(0)
	v_mfma_f32_16x16x32_bf16 v[18:21], v[22:25], v[18:21], 0
	ds_read_b128 v[22:25], v35 offset:64
	ds_read_b128 v[26:29], v26 offset:64
	v_add_u32_e32 v43, 0, v32
	v_add_u32_e32 v44, s53, v32
	v_mfma_f32_16x16x32_bf16 v[2:5], v[6:9], v[2:5], 0
	v_or_b32_e32 v6, v31, v37
	v_cmp_le_i32_e32 vcc, v6, v1
	s_mov_b32 s0, 0x800000
	v_mfma_f32_16x16x32_bf16 v[2:5], v[14:17], v[10:13], v[2:5]
	s_add_i32 s60, s60, 1
	s_cmp_eq_u32 s60, 4
	s_waitcnt lgkmcnt(0)
	v_mfma_f32_16x16x32_bf16 v[18:21], v[26:29], v[22:25], v[18:21]
	s_nop 3
	v_cndmask_b32_e32 v2, 0, v2, vcc
	v_cmp_lt_i32_e32 vcc, v6, v1
	s_nop 1
	v_cndmask_b32_e64 v7, v18, 0, vcc
	v_add_f32_e32 v2, v7, v2
	v_or_b32_e32 v7, 1, v6
	v_cndmask_b32_e32 v3, 0, v3, vcc
	v_cmp_ge_i32_e32 vcc, v7, v1
	s_nop 1
	v_cndmask_b32_e32 v7, 0, v19, vcc
	v_add_f32_e32 v3, v7, v3
	v_or_b32_e32 v7, 2, v6
	v_cmp_le_i32_e32 vcc, v7, v1
	v_or_b32_e32 v6, 3, v6
	v_cvt_pk_bf16_f32 v2, v2, v3
	s_nop 0
	v_cndmask_b32_e32 v4, 0, v4, vcc
	v_cmp_ge_i32_e32 vcc, v7, v1
	s_nop 1
	v_cndmask_b32_e32 v7, 0, v20, vcc
	v_cmp_le_i32_e32 vcc, v6, v1
	v_add_f32_e32 v4, v7, v4
	s_nop 0
	v_cndmask_b32_e32 v5, 0, v5, vcc
	v_cmp_ge_i32_e32 vcc, v6, v1
	s_nop 1
	v_cndmask_b32_e32 v6, 0, v21, vcc
	v_add_f32_e32 v5, v6, v5
	v_cvt_pk_bf16_f32 v3, v4, v5
	v_lshlrev_b32_e32 v4, 1, v31
	v_add3_u32 v39, v38, v39, v4
	v_or_b32_e32 v31, 16, v31
	ds_write_b64 v39, v[2:3] offset:36864
	v_or_b32_e32 v2, v31, v0
	v_mul_u32_u24_e32 v2, 0x48, v2
	v_lshlrev_b32_e32 v18, 1, v2
	v_add_u32_e32 v14, v34, v18
	ds_read_b128 v[2:5], v33
	ds_read_b128 v[6:9], v14
	ds_read_b128 v[10:13], v33 offset:64
	ds_read_b128 v[14:17], v14 offset:64
	v_add_u32_e32 v26, v36, v18
	ds_read_b128 v[18:21], v35
	ds_read_b128 v[22:25], v26
	s_waitcnt lgkmcnt(0)
	v_mfma_f32_16x16x32_bf16 v[18:21], v[22:25], v[18:21], 0
	ds_read_b128 v[22:25], v35 offset:64
	ds_read_b128 v[26:29], v26 offset:64
	v_mfma_f32_16x16x32_bf16 v[2:5], v[6:9], v[2:5], 0
	v_or_b32_e32 v6, v31, v37
	v_cmp_le_i32_e32 vcc, v6, v1
	v_mfma_f32_16x16x32_bf16 v[2:5], v[14:17], v[10:13], v[2:5]
	s_waitcnt lgkmcnt(0)
	v_mfma_f32_16x16x32_bf16 v[18:21], v[26:29], v[22:25], v[18:21]
	s_nop 5
	v_cndmask_b32_e32 v2, 0, v2, vcc
	v_cmp_lt_i32_e32 vcc, v6, v1
	s_nop 1
	v_cndmask_b32_e64 v7, v18, 0, vcc
	v_add_f32_e32 v2, v7, v2
	v_or_b32_e32 v7, 1, v6
	v_cndmask_b32_e32 v3, 0, v3, vcc
	v_cmp_ge_i32_e32 vcc, v7, v1
	s_nop 1
	v_cndmask_b32_e32 v7, 0, v19, vcc
	v_add_f32_e32 v3, v7, v3
	v_or_b32_e32 v7, 2, v6
	v_cmp_le_i32_e32 vcc, v7, v1
	v_or_b32_e32 v6, 3, v6
	v_cvt_pk_bf16_f32 v2, v2, v3
	s_nop 0
	v_cndmask_b32_e32 v4, 0, v4, vcc
	v_cmp_ge_i32_e32 vcc, v7, v1
	s_nop 1
	v_cndmask_b32_e32 v7, 0, v20, vcc
	v_cmp_le_i32_e32 vcc, v6, v1
	v_add_f32_e32 v4, v7, v4
	s_nop 0
	v_cndmask_b32_e32 v5, 0, v5, vcc
	v_cmp_ge_i32_e32 vcc, v6, v1
	s_nop 1
	v_cndmask_b32_e32 v6, 0, v21, vcc
	v_add_f32_e32 v5, v6, v5
	v_cvt_pk_bf16_f32 v3, v4, v5
	ds_write_b64 v39, v[2:3] offset:36896
	v_lshlrev_b32_e32 v2, 2, v30
	v_and_b32_e32 v42, 4, v2
	v_add_u32_e32 v30, v38, v32
	v_lshl_add_u32 v22, v1, 7, v30
	v_lshl_or_b32 v26, v42, 4, v0
	s_waitcnt lgkmcnt(0)
	s_barrier
	v_mad_u32_u24 v23, v26, s85, v43
	ds_read_b128 v[2:5], v22 offset:54272
	ds_read_b128 v[6:9], v23
	ds_read_b128 v[10:13], v22 offset:54336
	ds_read_b128 v[14:17], v23 offset:64
	s_waitcnt lgkmcnt(2)
	v_mfma_f32_16x16x32_bf16 v[6:9], v[6:9], v[2:5], 0
	v_mad_u32_u24 v31, v26, s87, v44
	v_or_b32_e32 v45, 1, v42
	v_lshl_or_b32 v38, v45, 4, v0
	s_waitcnt lgkmcnt(0)
	v_mfma_f32_16x16x32_bf16 v[6:9], v[14:17], v[10:13], v[6:9]
	ds_read_b128 v[14:17], v22 offset:54400
	ds_read_b128 v[18:21], v23 offset:128
	v_mad_u32_u24 v39, v38, s85, v43
	v_mad_u32_u24 v38, v38, s87, v44
	s_waitcnt lgkmcnt(0)
	v_mfma_f32_16x16x32_bf16 v[6:9], v[18:21], v[14:17], v[6:9]
	ds_read_b128 v[18:21], v22 offset:54464
	ds_read_b128 v[22:25], v23 offset:192
	v_or_b32_e32 v46, 2, v42
	v_lshl_or_b32 v47, v46, 4, v0
	s_waitcnt lgkmcnt(0)
	v_mfma_f32_16x16x32_bf16 v[6:9], v[22:25], v[18:21], v[6:9]
	ds_read_b128 v[22:25], v30 offset:36864
	ds_read_b128 v[26:29], v31
	v_mad_u32_u24 v48, v47, s85, v43
	v_mad_u32_u24 v47, v47, s87, v44
	s_waitcnt lgkmcnt(0)
	v_mfma_f32_16x16x32_bf16 v[6:9], v[26:29], v[22:25], v[6:9]
	ds_read_b128 v[26:29], v30 offset:36928
	ds_read_b128 v[30:33], v31 offset:64
	ds_read_b128 v[34:37], v39 offset:64
	s_waitcnt lgkmcnt(1)
	v_mfma_f32_16x16x32_bf16 v[6:9], v[30:33], v[26:29], v[6:9]
	ds_read_b128 v[30:33], v39
	s_waitcnt lgkmcnt(0)
	v_mfma_f32_16x16x32_bf16 v[30:33], v[30:33], v[2:5], 0
	v_mfma_f32_16x16x32_bf16 v[30:33], v[34:37], v[10:13], v[30:33]
	ds_read_b128 v[34:37], v39 offset:128
	s_waitcnt lgkmcnt(0)
	v_mfma_f32_16x16x32_bf16 v[30:33], v[34:37], v[14:17], v[30:33]
	ds_read_b128 v[34:37], v39 offset:192
	s_waitcnt lgkmcnt(0)
	v_mfma_f32_16x16x32_bf16 v[30:33], v[34:37], v[18:21], v[30:33]
	ds_read_b128 v[34:37], v38
	s_waitcnt lgkmcnt(0)
	v_mfma_f32_16x16x32_bf16 v[30:33], v[34:37], v[22:25], v[30:33]
	ds_read_b128 v[34:37], v38 offset:64
	ds_read_b128 v[38:41], v48 offset:64
	s_waitcnt lgkmcnt(1)
	v_mfma_f32_16x16x32_bf16 v[30:33], v[34:37], v[26:29], v[30:33]
	ds_read_b128 v[34:37], v48
	s_waitcnt lgkmcnt(0)
	v_mfma_f32_16x16x32_bf16 v[34:37], v[34:37], v[2:5], 0
	v_mfma_f32_16x16x32_bf16 v[34:37], v[38:41], v[10:13], v[34:37]
	ds_read_b128 v[38:41], v48 offset:128
	s_waitcnt lgkmcnt(0)
	v_mfma_f32_16x16x32_bf16 v[34:37], v[38:41], v[14:17], v[34:37]
	ds_read_b128 v[38:41], v48 offset:192
	s_waitcnt lgkmcnt(0)
	v_mfma_f32_16x16x32_bf16 v[34:37], v[38:41], v[18:21], v[34:37]
	ds_read_b128 v[38:41], v47
	s_waitcnt lgkmcnt(0)
	v_mfma_f32_16x16x32_bf16 v[34:37], v[38:41], v[22:25], v[34:37]
	ds_read_b128 v[38:41], v47 offset:64
	v_or_b32_e32 v47, 3, v42
	v_lshl_or_b32 v0, v47, 4, v0
	v_mad_u32_u24 v48, v0, s85, v43
	s_waitcnt lgkmcnt(0)
	v_mfma_f32_16x16x32_bf16 v[34:37], v[38:41], v[26:29], v[34:37]
	ds_read_b128 v[38:41], v48
	v_mad_u32_u24 v0, v0, s87, v44
	s_waitcnt lgkmcnt(0)
	v_mfma_f32_16x16x32_bf16 v[2:5], v[38:41], v[2:5], 0
	ds_read_b128 v[38:41], v48 offset:64
	s_waitcnt lgkmcnt(0)
	v_mfma_f32_16x16x32_bf16 v[2:5], v[38:41], v[10:13], v[2:5]
	ds_read_b128 v[10:13], v48 offset:128
	s_waitcnt lgkmcnt(0)
	v_mfma_f32_16x16x32_bf16 v[2:5], v[10:13], v[14:17], v[2:5]
	ds_read_b128 v[10:13], v48 offset:192
	s_waitcnt lgkmcnt(0)
	v_mfma_f32_16x16x32_bf16 v[2:5], v[10:13], v[18:21], v[2:5]
	ds_read_b128 v[10:13], v0
	s_waitcnt lgkmcnt(0)
	v_mfma_f32_16x16x32_bf16 v[2:5], v[10:13], v[22:25], v[2:5]
	ds_read_b128 v[10:13], v0 offset:64
	v_lshl_add_u32 v0, v1, 9, v43
	v_lshl_add_u32 v1, v42, 6, v0
	s_waitcnt lgkmcnt(0)
	v_mfma_f32_16x16x32_bf16 v[2:5], v[10:13], v[26:29], v[2:5]
	s_barrier
	ds_write_b128 v1, v[6:9] offset:54272
	v_lshl_add_u32 v1, v45, 6, v0
	ds_write_b128 v1, v[30:33] offset:54272
	v_lshl_add_u32 v1, v46, 6, v0
	v_lshl_add_u32 v0, v47, 6, v0
	s_nop 1
	ds_write_b128 v0, v[2:5] offset:54272
	v_lshlrev_b32_e32 v0, 9, v170
	v_lshlrev_b32_e32 v28, 2, v176
	v_add3_u32 v0, 0, v0, v28
	ds_write_b128 v1, v[34:37] offset:54272
	s_waitcnt lgkmcnt(0)
	s_barrier
	ds_read_b128 v[20:23], v0 offset:54272
	ds_read_b128 v[8:11], v0 offset:54288
	ds_read_b128 v[4:7], v0 offset:54304
	ds_read_b128 v[0:3], v0 offset:54320
	v_lshlrev_b32_e32 v176, 1, v176
	s_waitcnt lgkmcnt(3)
	v_mul_f32_e32 v14, v21, v21
	v_fmac_f32_e32 v14, v20, v20
	v_fmac_f32_e32 v14, v22, v22
	v_fmac_f32_e32 v14, v23, v23
	s_waitcnt lgkmcnt(2)
	v_fmac_f32_e32 v14, v8, v8
	v_fmac_f32_e32 v14, v9, v9
	v_fmac_f32_e32 v14, v10, v10
	v_fmac_f32_e32 v14, v11, v11
	s_waitcnt lgkmcnt(1)
	v_pk_mul_f32 v[12:13], v[4:5], v[4:5]
	s_nop 0
	v_add_f32_e32 v12, v14, v12
	v_add_f32_e32 v14, v12, v13
	v_pk_mul_f32 v[12:13], v[6:7], v[6:7]
	s_nop 0
	v_add_f32_e32 v12, v14, v12
	v_add_f32_e32 v14, v12, v13
	s_waitcnt lgkmcnt(0)
	v_pk_mul_f32 v[12:13], v[0:1], v[0:1]
	s_nop 0
	v_add_f32_e32 v12, v14, v12
	v_add_f32_e32 v14, v12, v13
	v_pk_mul_f32 v[12:13], v[2:3], v[2:3]
	s_nop 0
	v_add_f32_e32 v12, v14, v12
	v_and_b32_e32 v14, 64, v183
	v_add_f32_e32 v12, v12, v13
	v_xor_b32_e32 v13, 1, v183
	v_add_u32_e32 v14, 64, v14
	v_cmp_lt_i32_e32 vcc, v13, v14
	s_nop 1
	v_cndmask_b32_e32 v13, v183, v13, vcc
	v_lshlrev_b32_e32 v13, 2, v13
	ds_bpermute_b32 v13, v13, v12
	s_waitcnt lgkmcnt(0)
	v_add_f32_e32 v12, v12, v13
	v_xor_b32_e32 v13, 2, v183
	v_cmp_lt_i32_e32 vcc, v13, v14
	s_nop 1
	v_cndmask_b32_e32 v13, v183, v13, vcc
	v_lshlrev_b32_e32 v13, 2, v13
	ds_bpermute_b32 v13, v13, v12
	s_waitcnt lgkmcnt(0)
	v_add_f32_e32 v12, v12, v13
	v_xor_b32_e32 v13, 4, v183
	v_cmp_lt_i32_e32 vcc, v13, v14
	s_nop 1
	v_cndmask_b32_e32 v13, v183, v13, vcc
	v_lshlrev_b32_e32 v13, 2, v13
	ds_bpermute_b32 v13, v13, v12
	s_waitcnt lgkmcnt(0)
	v_add_f32_e32 v12, v12, v13
	v_fmamk_f32 v12, v12, 0x3c000000, v184
	v_cmp_gt_f32_e32 vcc, s0, v12
	v_mul_f32_e32 v13, 0x4b800000, v12
	s_mov_b64 s[0:1], 0x2000
	v_cndmask_b32_e32 v12, v12, v13, vcc
	v_rsq_f32_e32 v12, v12
	s_nop 0
	v_mul_f32_e32 v13, 0x45800000, v12
	v_cndmask_b32_e32 v32, v12, v13, vcc
	v_lshl_add_u64 v[12:13], v[118:119], 0, s[8:9]
	v_lshl_add_u64 v[12:13], v[12:13], 0, v[176:177]
	v_lshl_add_u64 v[16:17], v[12:13], 0, s[0:1]
	s_movk_i32 s0, 0x2000
	v_add_co_u32_e32 v12, vcc, s0, v12
	v_mul_f32_e32 v4, v4, v32
	s_nop 0
	v_addc_co_u32_e32 v13, vcc, 0, v13, vcc
	global_load_dwordx4 v[216:219], v[12:13], off
	s_nop 0
	global_load_dwordx4 v[220:223], v[16:17], off offset:16
	global_load_dwordx4 v[12:15], v28, s[30:31] offset:48
	global_load_dwordx4 v[16:19], v28, s[30:31] offset:32
	global_load_dwordx4 v[24:27], v28, s[30:31] offset:16
	global_load_dwordx4 v[28:31], v28, s[30:31]
	v_mul_f32_e32 v20, v20, v32
	v_mul_f32_e32 v8, v8, v32
	v_mul_f32_e32 v0, v0, v32
	v_mul_f32_e32 v21, v21, v32
	v_mul_f32_e32 v9, v9, v32
	v_mul_f32_e32 v22, v22, v32
	v_mul_f32_e32 v10, v10, v32
	v_mul_f32_e32 v23, v23, v32
	v_mul_f32_e32 v11, v11, v32
	s_waitcnt vmcnt(5)
	v_lshlrev_b32_e32 v46, 16, v216
	v_and_b32_e32 v47, 0xffff0000, v216
	v_lshlrev_b32_e32 v48, 16, v217
	v_and_b32_e32 v45, 0xffff0000, v217
	v_lshlrev_b32_e32 v44, 16, v218
	v_and_b32_e32 v43, 0xffff0000, v218
	v_lshlrev_b32_e32 v42, 16, v219
	v_and_b32_e32 v41, 0xffff0000, v219
	s_waitcnt vmcnt(4)
	v_lshlrev_b32_e32 v40, 16, v220
	v_and_b32_e32 v39, 0xffff0000, v220
	v_lshlrev_b32_e32 v38, 16, v221
	v_and_b32_e32 v37, 0xffff0000, v221
	v_lshlrev_b32_e32 v36, 16, v222
	v_and_b32_e32 v35, 0xffff0000, v222
	v_lshlrev_b32_e32 v34, 16, v223
	v_and_b32_e32 v33, 0xffff0000, v223
	s_waitcnt vmcnt(3)
	v_mul_f32_e32 v0, v0, v12
	s_waitcnt vmcnt(2)
	v_mul_f32_e32 v4, v4, v16
	v_mul_f32_e32 v16, 0xbfb8aa3b, v40
	v_exp_f32_e32 v16, v16
	s_waitcnt vmcnt(0)
	v_mul_f32_e32 v20, v28, v20
	v_mul_f32_e32 v28, 0xbfb8aa3b, v46
	v_mul_f32_e32 v8, v8, v24
	v_add_f32_e32 v16, 1.0, v16
	v_rcp_f32_e32 v16, v16
	v_mul_f32_e32 v24, 0xbfb8aa3b, v44
	v_exp_f32_e32 v28, v28
	v_exp_f32_e32 v24, v24
	v_mul_f32_e32 v16, v16, v40
	v_mul_f32_e32 v16, v16, v4
	v_mul_f32_e32 v4, v5, v32
	v_mul_f32_e32 v5, 0xbfb8aa3b, v39
	v_exp_f32_e32 v5, v5
	v_mul_f32_e32 v4, v4, v17
	v_add_f32_e32 v28, 1.0, v28
	v_add_f32_e32 v24, 1.0, v24
	v_add_f32_e32 v5, 1.0, v5
	v_rcp_f32_e32 v5, v5
	v_rcp_f32_e32 v28, v28
	v_rcp_f32_e32 v24, v24
	v_mul_f32_e32 v21, v21, v29
	v_mul_f32_e32 v5, v5, v39
	v_mul_f32_e32 v17, v5, v4
	v_mul_f32_e32 v5, 0xbfb8aa3b, v38
	v_exp_f32_e32 v5, v5
	v_mul_f32_e32 v4, v6, v32
	v_mul_f32_e32 v4, v4, v18
	v_mul_f32_e32 v28, v28, v46
	v_add_f32_e32 v5, 1.0, v5
	v_rcp_f32_e32 v5, v5
	v_mul_f32_e32 v24, v24, v44
	v_mul_f32_e32 v20, v28, v20
	v_mul_f32_e32 v28, 0xbfb8aa3b, v47
	v_mul_f32_e32 v5, v5, v38
	v_mul_f32_e32 v6, v5, v4
	v_mul_f32_e32 v5, 0xbfb8aa3b, v37
	v_exp_f32_e32 v5, v5
	v_mul_f32_e32 v4, v7, v32
	v_mul_f32_e32 v4, v4, v19
	v_mul_f32_e32 v8, v24, v8
	v_add_f32_e32 v5, 1.0, v5
	v_rcp_f32_e32 v5, v5
	v_mul_f32_e32 v24, 0xbfb8aa3b, v43
	v_exp_f32_e32 v28, v28
	v_exp_f32_e32 v24, v24
	v_mul_f32_e32 v5, v5, v37
	v_mul_f32_e32 v7, v5, v4
	v_mul_f32_e32 v4, 0xbfb8aa3b, v36
	v_exp_f32_e32 v4, v4
	v_add_f32_e32 v28, 1.0, v28
	v_add_f32_e32 v24, 1.0, v24
	v_rcp_f32_e32 v28, v28
	v_add_f32_e32 v4, 1.0, v4
	v_rcp_f32_e32 v4, v4
	v_rcp_f32_e32 v24, v24
	v_mul_f32_e32 v28, v28, v47
	v_mul_f32_e32 v9, v9, v25
	v_mul_f32_e32 v4, v4, v36
	v_mul_f32_e32 v12, v4, v0
	v_mul_f32_e32 v0, v1, v32
	v_mul_f32_e32 v1, 0xbfb8aa3b, v35
	v_exp_f32_e32 v1, v1
	v_mul_f32_e32 v0, v0, v13
	v_mul_f32_e32 v24, v24, v43
	v_mul_f32_e32 v21, v28, v21
	v_add_f32_e32 v1, 1.0, v1
	v_rcp_f32_e32 v1, v1
	v_mul_f32_e32 v28, 0xbfb8aa3b, v48
	v_mul_f32_e32 v9, v24, v9
	v_mul_f32_e32 v24, 0xbfb8aa3b, v42
	v_mul_f32_e32 v1, v1, v35
	v_mul_f32_e32 v13, v1, v0
	v_mul_f32_e32 v1, 0xbfb8aa3b, v34
	v_exp_f32_e32 v1, v1
	v_exp_f32_e32 v28, v28
	v_exp_f32_e32 v24, v24
	v_mul_f32_e32 v0, v2, v32
	v_add_f32_e32 v1, 1.0, v1
	v_rcp_f32_e32 v1, v1
	v_add_f32_e32 v28, 1.0, v28
	v_add_f32_e32 v24, 1.0, v24
	v_rcp_f32_e32 v28, v28
	v_rcp_f32_e32 v24, v24
	v_mul_f32_e32 v0, v0, v14
	v_mul_f32_e32 v1, v1, v34
	v_mul_f32_e32 v14, v1, v0
	v_mul_f32_e32 v1, 0xbfb8aa3b, v33
	v_mul_f32_e32 v22, v22, v30
	v_mul_f32_e32 v28, v28, v48
	v_mul_f32_e32 v10, v10, v26
	v_mul_f32_e32 v24, v24, v42
	v_exp_f32_e32 v1, v1
	v_mul_f32_e32 v22, v28, v22
	v_mul_f32_e32 v28, 0xbfb8aa3b, v45
	v_mul_f32_e32 v10, v24, v10
	v_mul_f32_e32 v24, 0xbfb8aa3b, v41
	v_exp_f32_e32 v28, v28
	v_exp_f32_e32 v24, v24
	v_add_f32_e32 v1, 1.0, v1
	v_rcp_f32_e32 v1, v1
	v_add_f32_e32 v28, 1.0, v28
	v_add_f32_e32 v24, 1.0, v24
	v_rcp_f32_e32 v28, v28
	v_rcp_f32_e32 v24, v24
	v_mul_f32_e32 v0, v3, v32
	v_mul_f32_e32 v0, v0, v15
	v_mul_f32_e32 v1, v1, v33
	v_mul_f32_e32 v15, v1, v0
	v_lshlrev_b64 v[0:1], 13, v[116:117]
	v_mul_f32_e32 v23, v23, v31
	v_mul_f32_e32 v28, v28, v45
	v_mul_f32_e32 v11, v11, v27
	v_mul_f32_e32 v24, v24, v41
	v_lshl_add_u64 v[0:1], s[4:5], 0, v[0:1]
	v_mul_f32_e32 v23, v28, v23
	v_mul_f32_e32 v11, v24, v11
	v_lshl_add_u64 v[4:5], v[0:1], 0, v[176:177]
	v_cvt_pk_bf16_f32 v0, v20, v21
	v_cvt_pk_bf16_f32 v1, v22, v23
	v_cvt_pk_bf16_f32 v2, v8, v9
	v_cvt_pk_bf16_f32 v3, v10, v11
	global_store_dwordx4 v[4:5], v[0:3], off offset:2048
	s_nop 1
	v_cvt_pk_bf16_f32 v0, v16, v17
	v_cvt_pk_bf16_f32 v1, v6, v7
	v_cvt_pk_bf16_f32 v2, v12, v13
	v_cvt_pk_bf16_f32 v3, v14, v15
	global_store_dwordx4 v[4:5], v[0:3], off offset:2064
	s_barrier
	s_cbranch_scc1 .LBB0_593
.LBB0_644:
	s_lshl_b32 s0, s60, 8
	s_add_i32 s12, s0, s54
	s_mul_i32 s0, s12, 0x8200
	v_mov_b32_e32 v171, v180
	s_mul_hi_i32 s1, s12, 0x8200
	s_add_u32 s0, s46, s0
	s_movk_i32 s2, 0x820
	s_addc_u32 s1, s47, s1
	v_lshlrev_b32_e32 v120, 2, v171
	v_lshlrev_b32_e32 v186, 4, v171
	v_ashrrev_i32_e32 v121, 31, v120
	global_load_dwordx4 v[188:191], v186, s[0:1]
	v_add_u32_e32 v172, 0x200, v171
	v_add_u32_e32 v187, 0x2000, v186
	v_lshlrev_b32_e32 v126, 2, v172
	global_load_dwordx4 v[192:195], v187, s[0:1]
	v_add_u32_e32 v173, 0x400, v171
	v_add_u32_e32 v187, 0x4000, v186
	v_lshlrev_b32_e32 v124, 2, v173
	global_load_dwordx4 v[196:199], v187, s[0:1]
	v_add_u32_e32 v174, 0x600, v171
	v_add_u32_e32 v187, 0x6000, v186
	v_lshlrev_b32_e32 v122, 2, v174
	global_load_dwordx4 v[200:203], v187, s[0:1]
	v_cmp_gt_i32_e32 vcc, 32, v171
	v_add_u32_e32 v187, 0x8000, v186
	s_nop 1
	v_cndmask_b32_e32 v187, 0, v187, vcc
	global_load_dwordx4 v[204:207], v187, s[0:1]
	s_ashr_i32 s61, s12, 3
	s_lshl_b32 s0, s61, 6
	s_cmp_lt_i32 s61, 64
	s_cselect_b64 s[20:21], -1, 0
	s_add_i32 s1, s0, 0xfffff000
	s_lshr_b32 s1, s1, 11
	s_ashr_i32 s2, s12, 5
	s_cmp_gt_i32 s61, 63
	v_readlane_b32 s68, v254, 12
	s_cselect_b64 s[24:25], -1, 0
	v_ashrrev_i32_e32 v170, 3, v171
	v_readlane_b32 s74, v254, 18
	v_readlane_b32 s75, v254, 19
	s_and_b64 vcc, s[24:25], exec
	v_add_u32_e32 v116, s0, v170
	v_mov_b64_e32 v[0:1], s[74:75]
	s_cselect_b32 s13, s1, s2
	v_and_b32_e32 v11, 7, v171
	v_mad_i64_i32 v[118:119], s[0:1], v116, s84, v[0:1]
	s_mov_b32 s7, s9
	v_lshl_add_u64 v[0:1], v[118:119], 0, s[6:7]
	v_lshlrev_b32_e32 v176, 4, v11
	v_lshl_add_u64 v[0:1], v[0:1], 0, v[176:177]
	v_add_co_u32_e64 v4, s[0:1], s92, v0
	s_nop 1
	v_addc_co_u32_e64 v5, s[0:1], 0, v1, s[0:1]
	global_load_dwordx4 v[208:211], v[4:5], off
	global_load_dwordx4 v[212:215], v[4:5], off offset:1024
	v_and_b32_e32 v232, 7, v171
	v_lshlrev_b32_e32 v232, 5, v232
	v_add_u32_e32 v232, s8, v232
	v_add_u32_e32 v232, 0x1800, v232
	v_mov_b32_e32 v233, 0
	v_lshl_add_u64 v[232:233], v[118:119], 0, v[232:233]
	global_load_dwordx4 v[224:227], v[232:233], off
	global_load_dwordx4 v[228:231], v[232:233], off offset:16
	s_waitcnt vmcnt(4)
	ds_write_b128 v186, v[188:191]
	ds_write_b128 v186, v[192:195] offset:8192
	ds_write_b128 v186, v[196:199] offset:16384
	ds_write_b128 v186, v[200:203] offset:24576
	v_cmp_gt_i32_e64 s[98:99], 32, v171
	s_and_saveexec_b64 s[62:63], s[98:99]
	ds_write_b128 v186, v[204:207] offset:32768
	s_mov_b64 exec, s[62:63]
	s_waitcnt lgkmcnt(0)
	s_barrier
	v_lshlrev_b32_e32 v8, 5, v11
	v_add_u32_e32 v10, 0, v8
	s_movk_i32 s0, 0x104
	v_mad_u64_u32 v[12:13], s[0:1], v170, s0, v[10:11]
	ds_read2_b32 v[14:15], v12 offset1:1
	v_add_u32_e32 v13, 0x607c, v10
	s_mov_b64 s[0:1], 0x1800
	v_mul_u32_u24_e32 v11, 0x900, v11
	s_lshl_b32 s14, s13, 2
	s_mov_b32 s15, s9
	s_mov_b32 s3, s9
	v_readlane_b32 s69, v254, 13
	v_readlane_b32 s70, v254, 14
	v_readlane_b32 s71, v254, 15
	v_readlane_b32 s72, v254, 16
	v_readlane_b32 s73, v254, 17
	v_readlane_b32 s76, v254, 20
	v_readlane_b32 s77, v254, 21
	v_readlane_b32 s78, v254, 22
	v_readlane_b32 s79, v254, 23
	v_readlane_b32 s80, v254, 24
	v_readlane_b32 s81, v254, 25
	v_readlane_b32 s82, v254, 26
	v_readlane_b32 s83, v254, 27
	s_waitcnt vmcnt(3)
	v_lshlrev_b32_e32 v6, 16, v208
	v_and_b32_e32 v20, 0xffff0000, v208
	v_lshlrev_b32_e32 v32, 16, v209
	v_and_b32_e32 v33, 0xffff0000, v209
	v_lshlrev_b32_e32 v40, 16, v210
	v_and_b32_e32 v41, 0xffff0000, v210
	v_lshlrev_b32_e32 v49, 16, v211
	v_and_b32_e32 v16, 0xffff0000, v211
	v_mul_f32_e32 v17, 0x3e000000, v6
	v_mul_f32_e32 v49, 0x3e000000, v49
	s_waitcnt vmcnt(2)
	v_lshlrev_b32_e32 v22, 16, v212
	v_and_b32_e32 v34, 0xffff0000, v212
	v_add_u32_e32 v0, 0x4100, v12
	v_lshlrev_b32_e32 v35, 16, v213
	v_and_b32_e32 v42, 0xffff0000, v213
	v_lshlrev_b32_e32 v37, 16, v214
	v_and_b32_e32 v50, 0xffff0000, v214
	v_lshlrev_b32_e32 v24, 16, v215
	v_and_b32_e32 v9, 0xffff0000, v215
	ds_read2_b32 v[28:29], v0 offset1:1
	ds_read_b128 v[4:7], v10 offset:8320
	ds_read_b128 v[0:3], v10 offset:8336
	ds_read2_b32 v[30:31], v13 offset1:1
	s_waitcnt lgkmcnt(4)
	v_mul_f32_e32 v13, 0x3fb8aa3b, v14
	v_exp_f32_e32 v13, v13
	s_nop 0
	v_mul_f32_e32 v23, v17, v13
	s_waitcnt lgkmcnt(3)
	v_mul_f32_e32 v13, 0x3fb8aa3b, v28
	v_exp_f32_e32 v13, v13
	s_nop 0
	v_mul_f32_e32 v21, v17, v13
	s_waitcnt lgkmcnt(2)
	v_sub_f32_e32 v13, v14, v4
	v_sub_f32_e32 v4, v4, v14
	v_mul_f32_e32 v4, 0x3fb8aa3b, v4
	v_exp_f32_e32 v4, v4
	v_mul_f32_e32 v13, 0x3fb8aa3b, v13
	v_exp_f32_e32 v13, v13
	v_mul_f32_e32 v14, 0x3fb8aa3b, v15
	v_mul_f32_e32 v18, v4, v22
	s_waitcnt lgkmcnt(0)
	v_sub_f32_e32 v4, v28, v30
	v_mul_f32_e32 v4, 0x3fb8aa3b, v4
	v_exp_f32_e32 v4, v4
	v_mul_f32_e32 v19, v17, v13
	v_exp_f32_e32 v14, v14
	v_mul_f32_e32 v17, v17, v4
	v_sub_f32_e32 v4, v30, v28
	v_mul_f32_e32 v4, 0x3fb8aa3b, v4
	v_exp_f32_e32 v4, v4
	s_nop 0
	v_mul_f32_e32 v13, v4, v22
	v_mul_f32_e32 v4, 0x3e000000, v20
	v_mul_f32_e32 v28, v4, v14
	v_mul_f32_e32 v14, 0x3fb8aa3b, v29
	v_exp_f32_e32 v14, v14
	s_nop 0
	v_mul_f32_e32 v27, v4, v14
	v_sub_f32_e32 v14, v15, v5
	v_sub_f32_e32 v5, v5, v15
	v_mul_f32_e32 v5, 0x3fb8aa3b, v5
	v_exp_f32_e32 v5, v5
	v_mul_f32_e32 v14, 0x3fb8aa3b, v14
	v_exp_f32_e32 v14, v14
	v_mul_f32_e32 v25, v5, v34
	v_sub_f32_e32 v5, v29, v31
	v_mul_f32_e32 v5, 0x3fb8aa3b, v5
	v_exp_f32_e32 v5, v5
	v_mul_f32_e32 v26, v4, v14
	ds_read2_b32 v[14:15], v12 offset0:2 offset1:3
	v_mul_f32_e32 v22, v4, v5
	v_sub_f32_e32 v4, v31, v29
	v_mul_f32_e32 v4, 0x3fb8aa3b, v4
	v_exp_f32_e32 v4, v4
	v_add_u32_e32 v29, 0x6084, v10
	ds_read2_b32 v[38:39], v29 offset1:1
	v_mul_f32_e32 v20, v4, v34
	v_add_u32_e32 v4, 0x4108, v12
	ds_read2_b32 v[4:5], v4 offset1:1
	s_waitcnt lgkmcnt(2)
	v_mul_f32_e32 v29, 0x3fb8aa3b, v14
	v_exp_f32_e32 v29, v29
	v_mul_f32_e32 v34, 0x3e000000, v32
	v_mul_f32_e32 v32, v34, v29
	s_waitcnt lgkmcnt(0)
	v_mul_f32_e32 v29, 0x3fb8aa3b, v4
	v_exp_f32_e32 v29, v29
	s_nop 0
	v_mul_f32_e32 v31, v34, v29
	v_sub_f32_e32 v29, v14, v6
	v_sub_f32_e32 v6, v6, v14
	v_mul_f32_e32 v29, 0x3fb8aa3b, v29
	v_mul_f32_e32 v6, 0x3fb8aa3b, v6
	v_exp_f32_e32 v29, v29
	v_exp_f32_e32 v6, v6
	v_mul_f32_e32 v30, v34, v29
	v_mul_f32_e32 v29, v6, v35
	v_sub_f32_e32 v6, v4, v38
	v_sub_f32_e32 v4, v38, v4
	v_mul_f32_e32 v6, 0x3fb8aa3b, v6
	v_mul_f32_e32 v4, 0x3fb8aa3b, v4
	v_exp_f32_e32 v6, v6
	v_exp_f32_e32 v4, v4
	v_mul_f32_e32 v38, 0x3e000000, v40
	v_mul_f32_e32 v14, v34, v6
	v_mul_f32_e32 v6, v4, v35
	v_mul_f32_e32 v4, 0x3e000000, v33
	v_mul_f32_e32 v33, 0x3fb8aa3b, v15
	v_exp_f32_e32 v33, v33
	s_nop 0
	v_mul_f32_e32 v36, v4, v33
	v_mul_f32_e32 v33, 0x3fb8aa3b, v5
	v_exp_f32_e32 v33, v33
	s_nop 0
	v_mul_f32_e32 v35, v4, v33
	v_sub_f32_e32 v33, v15, v7
	v_sub_f32_e32 v7, v7, v15
	v_mul_f32_e32 v33, 0x3fb8aa3b, v33
	v_mul_f32_e32 v7, 0x3fb8aa3b, v7
	v_exp_f32_e32 v33, v33
	v_exp_f32_e32 v7, v7
	v_mul_f32_e32 v34, v4, v33
	v_mul_f32_e32 v33, v7, v42
	v_sub_f32_e32 v7, v5, v39
	v_mul_f32_e32 v7, 0x3fb8aa3b, v7
	v_exp_f32_e32 v7, v7
	s_nop 0
	v_mul_f32_e32 v15, v4, v7
	v_sub_f32_e32 v4, v39, v5
	v_mul_f32_e32 v4, 0x3fb8aa3b, v4
	v_exp_f32_e32 v4, v4
	v_add_u32_e32 v39, 0x4110, v12
	ds_read2_b32 v[52:53], v39 offset1:1
	v_add_u32_e32 v39, 0x608c, v10
	v_mul_f32_e32 v7, v4, v42
	ds_read2_b32 v[4:5], v12 offset0:4 offset1:5
	ds_read2_b32 v[54:55], v39 offset1:1
	v_add_u32_e32 v10, 0x6094, v10
	s_waitcnt lgkmcnt(1)
	v_mul_f32_e32 v39, 0x3fb8aa3b, v4
	v_exp_f32_e32 v39, v39
	s_nop 0
	v_mul_f32_e32 v44, v38, v39
	v_mul_f32_e32 v39, 0x3fb8aa3b, v52
	v_exp_f32_e32 v39, v39
	s_nop 0
	v_mul_f32_e32 v42, v38, v39
	v_sub_f32_e32 v39, v4, v0
	v_sub_f32_e32 v0, v0, v4
	v_mul_f32_e32 v39, 0x3fb8aa3b, v39
	v_mul_f32_e32 v0, 0x3fb8aa3b, v0
	v_exp_f32_e32 v39, v39
	v_exp_f32_e32 v0, v0
	v_mul_f32_e32 v4, 0x3fb8aa3b, v5
	v_exp_f32_e32 v4, v4
	v_mul_f32_e32 v40, v38, v39
	v_mul_f32_e32 v39, v0, v37
	s_waitcnt lgkmcnt(0)
	v_sub_f32_e32 v0, v52, v54
	v_mul_f32_e32 v0, 0x3fb8aa3b, v0
	v_exp_f32_e32 v0, v0
	s_nop 0
	v_mul_f32_e32 v38, v38, v0
	v_sub_f32_e32 v0, v54, v52
	v_mul_f32_e32 v0, 0x3fb8aa3b, v0
	v_exp_f32_e32 v0, v0
	s_nop 0
	v_mul_f32_e32 v37, v0, v37
	v_mul_f32_e32 v0, 0x3e000000, v41
	v_mul_f32_e32 v48, v0, v4
	v_mul_f32_e32 v4, 0x3fb8aa3b, v53
	v_exp_f32_e32 v4, v4
	s_nop 0
	v_mul_f32_e32 v47, v0, v4
	v_sub_f32_e32 v4, v5, v1
	v_sub_f32_e32 v1, v1, v5
	v_mul_f32_e32 v1, 0x3fb8aa3b, v1
	v_exp_f32_e32 v1, v1
	v_mul_f32_e32 v4, 0x3fb8aa3b, v4
	v_exp_f32_e32 v4, v4
	v_mul_f32_e32 v45, v1, v50
	v_sub_f32_e32 v1, v53, v55
	v_mul_f32_e32 v1, 0x3fb8aa3b, v1
	v_exp_f32_e32 v1, v1
	v_mul_f32_e32 v46, v0, v4
	v_add_u32_e32 v4, 0x4118, v12
	ds_read2_b32 v[4:5], v4 offset1:1
	v_mul_f32_e32 v43, v0, v1
	v_sub_f32_e32 v0, v55, v53
	v_mul_f32_e32 v0, 0x3fb8aa3b, v0
	v_exp_f32_e32 v0, v0
	s_nop 0
	v_mul_f32_e32 v41, v0, v50
	ds_read2_b32 v[0:1], v12 offset0:6 offset1:7
	ds_read2_b32 v[50:51], v10 offset1:1
	s_waitcnt lgkmcnt(2)
	v_mul_f32_e32 v12, 0x3fb8aa3b, v4
	v_exp_f32_e32 v12, v12
	s_waitcnt lgkmcnt(1)
	v_mul_f32_e32 v10, 0x3fb8aa3b, v0
	v_sub_f32_e32 v52, v0, v2
	v_sub_f32_e32 v0, v2, v0
	v_mul_f32_e32 v0, 0x3fb8aa3b, v0
	v_exp_f32_e32 v0, v0
	v_mul_f32_e32 v52, 0x3fb8aa3b, v52
	v_exp_f32_e32 v10, v10
	v_exp_f32_e32 v52, v52
	v_mul_f32_e32 v53, v0, v24
	s_waitcnt lgkmcnt(0)
	v_sub_f32_e32 v0, v4, v50
	v_mul_f32_e32 v0, 0x3fb8aa3b, v0
	v_exp_f32_e32 v0, v0
	v_mul_f32_e32 v10, v49, v10
	v_mul_f32_e32 v12, v49, v12
	v_mul_f32_e32 v52, v49, v52
	v_mul_f32_e32 v49, v49, v0
	v_sub_f32_e32 v0, v50, v4
	v_mul_f32_e32 v0, 0x3fb8aa3b, v0
	v_exp_f32_e32 v0, v0
	v_mul_f32_e32 v2, 0x3fb8aa3b, v1
	v_exp_f32_e32 v2, v2
	v_mul_f32_e32 v4, v0, v24
	v_mul_f32_e32 v0, 0x3e000000, v16
	v_mul_f32_e32 v16, v0, v2
	v_mul_f32_e32 v2, 0x3fb8aa3b, v5
	v_exp_f32_e32 v2, v2
	s_nop 0
	v_mul_f32_e32 v24, v0, v2
	v_sub_f32_e32 v2, v1, v3
	v_sub_f32_e32 v1, v3, v1
	v_mul_f32_e32 v1, 0x3fb8aa3b, v1
	v_exp_f32_e32 v1, v1
	v_mul_f32_e32 v2, 0x3fb8aa3b, v2
	v_exp_f32_e32 v2, v2
	v_mul_f32_e32 v54, v1, v9
	v_sub_f32_e32 v1, v5, v51
	v_mul_f32_e32 v1, 0x3fb8aa3b, v1
	v_exp_f32_e32 v1, v1
	v_mul_f32_e32 v50, v0, v2
	v_mul_f32_e32 v55, v0, v1
	v_sub_f32_e32 v0, v51, v5
	v_mul_f32_e32 v0, 0x3fb8aa3b, v0
	v_exp_f32_e32 v0, v0
	s_nop 0
	v_mul_f32_e32 v5, v0, v9
	v_mul_lo_u32 v9, v170, s85
	v_cvt_pk_bf16_f32 v0, v23, v28
	v_cvt_pk_bf16_f32 v1, v32, v36
	v_cvt_pk_bf16_f32 v2, v44, v48
	v_cvt_pk_bf16_f32 v3, v10, v16
	v_add3_u32 v9, 0, v9, v176
	ds_write_b128 v9, v[0:3] offset:54272
	v_cvt_pk_bf16_f32 v0, v21, v27
	v_cvt_pk_bf16_f32 v1, v31, v35
	v_cvt_pk_bf16_f32 v2, v42, v47
	v_cvt_pk_bf16_f32 v3, v12, v24
	ds_write_b128 v9, v[0:3] offset:54400
	v_mul_lo_u32 v9, v170, s87
	v_cvt_pk_bf16_f32 v0, v19, v26
	v_cvt_pk_bf16_f32 v1, v30, v34
	v_cvt_pk_bf16_f32 v2, v40, v46
	v_cvt_pk_bf16_f32 v3, v52, v50
	v_add3_u32 v10, s86, v9, v176
	ds_write_b128 v10, v[0:3]
	v_cvt_pk_bf16_f32 v0, v18, v25
	v_cvt_pk_bf16_f32 v1, v29, v33
	v_cvt_pk_bf16_f32 v2, v39, v45
	v_cvt_pk_bf16_f32 v3, v53, v54
	v_add3_u32 v10, s88, v9, v176
	ds_write_b128 v10, v[0:3]
	v_cvt_pk_bf16_f32 v0, v17, v22
	v_cvt_pk_bf16_f32 v1, v14, v15
	v_cvt_pk_bf16_f32 v2, v38, v43
	v_cvt_pk_bf16_f32 v3, v49, v55
	v_add3_u32 v10, s89, v9, v176
	ds_write_b128 v10, v[0:3]
	v_cvt_pk_bf16_f32 v0, v13, v20
	v_cvt_pk_bf16_f32 v1, v6, v7
	v_cvt_pk_bf16_f32 v2, v37, v41
	v_cvt_pk_bf16_f32 v3, v4, v5
	v_add3_u32 v4, s52, v9, v176
	ds_write_b128 v4, v[0:3]
	v_lshl_add_u64 v[0:1], v[118:119], 0, s[8:9]
	v_mov_b32_e32 v9, v177
	v_lshl_add_u64 v[0:1], v[0:1], 0, v[8:9]
	v_lshl_add_u64 v[4:5], v[0:1], 0, s[0:1]
	v_add_co_u32_e64 v0, s[0:1], s92, v0
	v_lshlrev_b32_e32 v17, 1, v170
	s_nop 0
	v_addc_co_u32_e64 v1, s[0:1], 0, v1, s[0:1]
	s_waitcnt vmcnt(0)
	v_mov_b32_e32 v0, v224
	v_mov_b32_e32 v1, v225
	v_mov_b32_e32 v2, v226
	v_mov_b32_e32 v3, v227
	v_mov_b32_e32 v4, v228
	v_mov_b32_e32 v5, v229
	v_mov_b32_e32 v6, v230
	v_mov_b32_e32 v7, v231
	v_add3_u32 v11, s53, v17, v11
	s_lshl_b64 s[0:1], s[14:15], 18
	s_add_u32 s0, s56, s0
	s_addc_u32 s1, s57, s1
	s_or_b32 s2, s14, 1
	s_waitcnt vmcnt(1)
	v_lshlrev_b32_e32 v8, 16, v0
	v_and_b32_e32 v0, 0xffff0000, v0
	v_cvt_pk_bf16_f32 v8, v8, v177
	ds_write_b16 v11, v8
	v_cvt_pk_bf16_f32 v0, v0, v177
	v_lshlrev_b32_e32 v9, 16, v1
	ds_write_b16 v11, v0 offset:144
	v_cvt_pk_bf16_f32 v0, v9, v177
	v_and_b32_e32 v1, 0xffff0000, v1
	ds_write_b16 v11, v0 offset:288
	v_cvt_pk_bf16_f32 v0, v1, v177
	v_lshlrev_b32_e32 v10, 16, v2
	ds_write_b16 v11, v0 offset:432
	v_cvt_pk_bf16_f32 v0, v10, v177
	v_and_b32_e32 v2, 0xffff0000, v2
	ds_write_b16 v11, v0 offset:576
	v_cvt_pk_bf16_f32 v0, v2, v177
	v_lshlrev_b32_e32 v12, 16, v3
	ds_write_b16 v11, v0 offset:720
	v_cvt_pk_bf16_f32 v0, v12, v177
	v_and_b32_e32 v3, 0xffff0000, v3
	ds_write_b16 v11, v0 offset:864
	v_cvt_pk_bf16_f32 v0, v3, v177
	s_waitcnt vmcnt(0)
	v_lshlrev_b32_e32 v13, 16, v4
	ds_write_b16 v11, v0 offset:1008
	v_cvt_pk_bf16_f32 v0, v13, v177
	v_and_b32_e32 v4, 0xffff0000, v4
	ds_write_b16 v11, v0 offset:1152
	v_cvt_pk_bf16_f32 v0, v4, v177
	v_lshlrev_b32_e32 v14, 16, v5
	ds_write_b16 v11, v0 offset:1296
	v_cvt_pk_bf16_f32 v0, v14, v177
	v_and_b32_e32 v5, 0xffff0000, v5
	ds_write_b16 v11, v0 offset:1440
	v_cvt_pk_bf16_f32 v0, v5, v177
	v_lshlrev_b32_e32 v15, 16, v6
	ds_write_b16 v11, v0 offset:1584
	v_cvt_pk_bf16_f32 v0, v15, v177
	v_and_b32_e32 v6, 0xffff0000, v6
	ds_write_b16 v11, v0 offset:1728
	v_cvt_pk_bf16_f32 v0, v6, v177
	v_lshlrev_b32_e32 v16, 16, v7
	ds_write_b16 v11, v0 offset:1872
	v_cvt_pk_bf16_f32 v0, v16, v177
	v_and_b32_e32 v7, 0xffff0000, v7
	ds_write_b16 v11, v0 offset:2016
	v_cvt_pk_bf16_f32 v0, v7, v177
	ds_write_b16 v11, v0 offset:2160
	v_lshlrev_b32_e32 v0, 11, v171
	v_and_b32_e32 v2, 0x7800, v0
	v_mov_b32_e32 v3, v177
	v_lshl_add_u64 v[0:1], s[0:1], 0, v[2:3]
	s_lshl_b64 s[0:1], s[2:3], 18
	s_add_u32 s0, s56, s0
	s_addc_u32 s1, s57, s1
	v_lshl_add_u64 v[2:3], s[0:1], 0, v[2:3]
	s_cbranch_vccz .LBB0_659
	v_readlane_b32 s68, v254, 16
	v_readlane_b32 s69, v254, 17
	s_sub_i32 s70, s61, 64
	s_lshl_b32 s70, s70, 3
	s_or_b32 s70, s70, s55
	s_mov_b32 s71, 0
	s_lshl_b64 s[70:71], s[70:71], 16
	s_add_u32 s68, s68, s70
	s_addc_u32 s69, s69, s71
	s_add_u32 s70, s68, 0x8000
	s_addc_u32 s71, s69, 0
	v_lshlrev_b32_e32 v186, 4, v171
	global_load_dwordx4 v[132:135], v186, s[68:69]
	global_load_dwordx4 v[128:131], v186, s[70:71]
	v_add_u32_e32 v187, 0x2000, v186
	global_load_dwordx4 v[140:143], v187, s[68:69]
	global_load_dwordx4 v[136:139], v187, s[70:71]
	v_add_u32_e32 v187, 0x4000, v186
	global_load_dwordx4 v[148:151], v187, s[68:69]
	global_load_dwordx4 v[144:147], v187, s[70:71]
	v_add_u32_e32 v187, 0x6000, v186
	global_load_dwordx4 v[156:159], v187, s[68:69]
	global_load_dwordx4 v[152:155], v187, s[70:71]
	v_ashrrev_i32_e32 v117, 31, v116
	s_branch .LBB0_643
	v_ashrrev_i32_e32 v4, 4, v171
	v_ashrrev_i32_e32 v5, 31, v4
	v_lshlrev_b64 v[4:5], 2, v[4:5]
	v_lshl_add_u64 v[6:7], v[0:1], 0, v[4:5]
	v_lshl_add_u64 v[4:5], v[2:3], 0, v[4:5]
	global_load_dword v132, v[6:7], off
	global_load_dword v133, v[6:7], off offset:512
	global_load_dword v134, v[6:7], off offset:1024
	global_load_dword v135, v[6:7], off offset:1536
	global_load_dword v128, v[4:5], off
	global_load_dword v129, v[4:5], off offset:512
	global_load_dword v130, v[4:5], off offset:1024
	global_load_dword v131, v[4:5], off offset:1536
	v_cndmask_b32_e64 v4, 0, 1, s[24:25]
	v_cmp_ne_u32_e64 s[0:1], 1, v4
	s_andn2_b64 vcc, exec, s[24:25]
	s_cbranch_vccz .LBB0_660

.LBB0_1355:
	s_lshl_b32 s0, s29, 8
	s_add_i32 s12, s0, s60
	s_mul_i32 s0, s12, 0x8200
	v_mov_b32_e32 v171, v180
	s_mul_hi_i32 s1, s12, 0x8200
	s_add_u32 s0, s46, s0
	s_movk_i32 s2, 0x820
	s_addc_u32 s1, s47, s1
	v_lshlrev_b32_e32 v120, 2, v171
	v_lshlrev_b32_e32 v186, 4, v171
	v_ashrrev_i32_e32 v121, 31, v120
	global_load_dwordx4 v[188:191], v186, s[0:1]
	v_add_u32_e32 v172, 0x200, v171
	v_add_u32_e32 v187, 0x2000, v186
	v_lshlrev_b32_e32 v126, 2, v172
	global_load_dwordx4 v[192:195], v187, s[0:1]
	v_add_u32_e32 v173, 0x400, v171
	v_add_u32_e32 v187, 0x4000, v186
	v_lshlrev_b32_e32 v124, 2, v173
	global_load_dwordx4 v[196:199], v187, s[0:1]
	v_add_u32_e32 v174, 0x600, v171
	v_add_u32_e32 v187, 0x6000, v186
	v_lshlrev_b32_e32 v122, 2, v174
	global_load_dwordx4 v[200:203], v187, s[0:1]
	v_cmp_gt_i32_e32 vcc, 32, v171
	v_add_u32_e32 v187, 0x8000, v186
	s_nop 1
	v_cndmask_b32_e32 v187, 0, v187, vcc
	global_load_dwordx4 v[204:207], v187, s[0:1]
	s_ashr_i32 s61, s12, 3
	v_readlane_b32 s64, v254, 12
	s_lshl_b32 s0, s61, 6
	v_ashrrev_i32_e32 v170, 3, v171
	v_readlane_b32 s70, v254, 18
	v_readlane_b32 s71, v254, 19
	v_add_u32_e32 v116, s0, v170
	v_and_b32_e32 v19, 7, v171
	v_mov_b64_e32 v[0:1], s[70:71]
	v_mad_i64_i32 v[118:119], s[2:3], v116, s52, v[0:1]
	s_mov_b32 s7, s9
	v_lshl_add_u64 v[0:1], v[118:119], 0, s[6:7]
	v_lshlrev_b32_e32 v176, 4, v19
	v_lshl_add_u64 v[0:1], v[0:1], 0, v[176:177]
	v_add_co_u32_e32 v0, vcc, s34, v0
	s_nop 1
	v_addc_co_u32_e32 v1, vcc, 0, v1, vcc
	global_load_dwordx4 v[4:7], v[0:1], off
	global_load_dwordx4 v[8:11], v[0:1], off offset:1024
	v_and_b32_e32 v232, 7, v171
	v_lshlrev_b32_e32 v232, 5, v232
	v_add_u32_e32 v232, s8, v232
	v_add_u32_e32 v232, 0x1800, v232
	v_mov_b32_e32 v233, 0
	v_lshl_add_u64 v[232:233], v[118:119], 0, v[232:233]
	global_load_dwordx4 v[224:227], v[232:233], off
	global_load_dwordx4 v[228:231], v[232:233], off offset:16
	s_waitcnt vmcnt(4)
	ds_write_b128 v186, v[188:191]
	ds_write_b128 v186, v[192:195] offset:8192
	ds_write_b128 v186, v[196:199] offset:16384
	ds_write_b128 v186, v[200:203] offset:24576
	v_cmp_gt_i32_e64 s[98:99], 32, v171
	s_and_saveexec_b64 s[62:63], s[98:99]
	ds_write_b128 v186, v[204:207] offset:32768
	s_mov_b64 exec, s[62:63]
	s_waitcnt lgkmcnt(0)
	s_barrier
	v_lshlrev_b32_e32 v16, 5, v19
	v_add_u32_e32 v18, 0, v16
	ds_read_b128 v[12:15], v18 offset:8320
	ds_read_b128 v[0:3], v18 offset:8336
	s_movk_i32 s1, 0x104
	v_mad_u64_u32 v[20:21], s[2:3], v170, s1, v[18:19]
	v_add_u32_e32 v21, 0x6084, v18
	v_add_u32_e32 v17, 0x607c, v18
	v_add_u32_e32 v30, 0x4100, v20
	v_add_u32_e32 v31, 0x4108, v20
	ds_read2_b32 v[28:29], v20 offset1:1
	ds_read2_b32 v[26:27], v20 offset0:2 offset1:3
	ds_read2_b32 v[24:25], v20 offset0:4 offset1:5
	ds_read2_b32 v[22:23], v20 offset0:6 offset1:7
	ds_read2_b32 v[32:33], v30 offset1:1
	ds_read2_b32 v[34:35], v17 offset1:1
	ds_read2_b32 v[40:41], v31 offset1:1
	ds_read2_b32 v[42:43], v21 offset1:1
	s_waitcnt lgkmcnt(7)
	v_sub_f32_e32 v21, v28, v12
	v_sub_f32_e32 v12, v12, v28
	v_mul_f32_e32 v12, 0x3fb8aa3b, v12
	v_exp_f32_e32 v12, v12
	v_mul_f32_e32 v17, 0x3fb8aa3b, v28
	v_mul_f32_e32 v28, 0x3fb8aa3b, v29
	v_sub_f32_e32 v30, v29, v13
	v_sub_f32_e32 v37, v13, v29
	v_exp_f32_e32 v13, v17
	s_waitcnt lgkmcnt(3)
	v_mul_f32_e32 v17, 0x3fb8aa3b, v32
	s_waitcnt lgkmcnt(2)
	v_sub_f32_e32 v29, v32, v34
	v_sub_f32_e32 v31, v34, v32
	v_exp_f32_e32 v32, v28
	v_mul_f32_e32 v21, 0x3fb8aa3b, v21
	v_mul_f32_e32 v30, 0x3fb8aa3b, v30
	v_mul_f32_e32 v29, 0x3fb8aa3b, v29
	v_mul_f32_e32 v31, 0x3fb8aa3b, v31
	v_exp_f32_e32 v21, v21
	v_exp_f32_e32 v30, v30
	v_exp_f32_e32 v38, v29
	v_exp_f32_e32 v29, v31
	v_mul_f32_e32 v28, 0x3fb8aa3b, v33
	v_exp_f32_e32 v17, v17
	v_exp_f32_e32 v34, v28
	s_mov_b64 s[2:3], 0x1800
	s_cmp_lt_i32 s61, 64
	s_mov_b32 s17, s9
	s_mov_b32 s15, s9
	v_readlane_b32 s65, v254, 13
	v_readlane_b32 s66, v254, 14
	v_readlane_b32 s67, v254, 15
	v_readlane_b32 s68, v254, 16
	v_readlane_b32 s69, v254, 17
	v_readlane_b32 s72, v254, 20
	v_readlane_b32 s73, v254, 21
	v_readlane_b32 s74, v254, 22
	v_readlane_b32 s75, v254, 23
	v_readlane_b32 s76, v254, 24
	v_readlane_b32 s77, v254, 25
	v_readlane_b32 s78, v254, 26
	v_readlane_b32 s79, v254, 27
	s_waitcnt vmcnt(3)
	v_lshlrev_b32_e32 v46, 16, v6
	v_and_b32_e32 v47, 0xffff0000, v6
	s_waitcnt vmcnt(2)
	v_lshlrev_b32_e32 v6, 16, v8
	v_lshlrev_b32_e32 v31, 16, v4
	v_and_b32_e32 v4, 0xffff0000, v4
	v_and_b32_e32 v45, 0xffff0000, v8
	v_mul_f32_e32 v8, v12, v6
	v_sub_f32_e32 v12, v35, v33
	v_lshlrev_b32_e32 v49, 16, v9
	v_and_b32_e32 v50, 0xffff0000, v9
	v_mul_f32_e32 v4, 0x3e000000, v4
	v_mul_f32_e32 v9, 0x3fb8aa3b, v37
	v_mul_f32_e32 v12, 0x3fb8aa3b, v12
	v_lshlrev_b32_e32 v48, 16, v7
	v_and_b32_e32 v36, 0xffff0000, v7
	v_lshlrev_b32_e32 v51, 16, v10
	v_and_b32_e32 v52, 0xffff0000, v10
	v_mul_f32_e32 v7, 0x3e000000, v31
	v_mul_f32_e32 v31, v4, v32
	v_exp_f32_e32 v9, v9
	v_sub_f32_e32 v10, v33, v35
	v_exp_f32_e32 v32, v12
	v_mul_f32_e32 v10, 0x3fb8aa3b, v10
	v_sub_f32_e32 v33, v26, v14
	v_sub_f32_e32 v14, v14, v26
	v_lshlrev_b32_e32 v39, 16, v11
	v_and_b32_e32 v28, 0xffff0000, v11
	v_mul_f32_e32 v11, v7, v21
	v_exp_f32_e32 v10, v10
	v_mul_f32_e32 v21, v4, v30
	v_mul_f32_e32 v30, 0x3fb8aa3b, v26
	v_mul_f32_e32 v14, 0x3fb8aa3b, v14
	v_exp_f32_e32 v30, v30
	v_exp_f32_e32 v14, v14
	v_mul_f32_e32 v12, v9, v45
	v_mul_f32_e32 v9, v32, v45
	s_waitcnt lgkmcnt(1)
	v_mul_f32_e32 v32, 0x3fb8aa3b, v40
	v_mul_f32_e32 v33, 0x3fb8aa3b, v33
	v_lshlrev_b32_e32 v44, 16, v5
	v_exp_f32_e32 v32, v32
	v_exp_f32_e32 v35, v33
	v_mul_f32_e32 v6, v29, v6
	v_mul_f32_e32 v29, v7, v13
	v_mul_f32_e32 v13, v7, v17
	v_mul_f32_e32 v17, v4, v34
	v_mul_f32_e32 v10, v4, v10
	v_mul_f32_e32 v4, 0x3e000000, v44
	v_mul_f32_e32 v34, v4, v30
	v_mul_f32_e32 v30, v14, v49
	s_waitcnt lgkmcnt(0)
	v_sub_f32_e32 v14, v40, v42
	v_sub_f32_e32 v26, v42, v40
	v_mul_f32_e32 v14, 0x3fb8aa3b, v14
	v_mul_f32_e32 v26, 0x3fb8aa3b, v26
	v_mul_f32_e32 v33, v4, v32
	v_mul_f32_e32 v32, v4, v35
	v_exp_f32_e32 v14, v14
	v_exp_f32_e32 v35, v26
	v_mul_f32_e32 v26, 0x3fb8aa3b, v27
	v_and_b32_e32 v5, 0xffff0000, v5
	v_exp_f32_e32 v37, v26
	v_mul_f32_e32 v26, v4, v14
	v_mul_f32_e32 v14, v35, v49
	v_sub_f32_e32 v35, v27, v15
	v_sub_f32_e32 v15, v15, v27
	v_sub_f32_e32 v27, v41, v43
	v_mul_f32_e32 v4, 0x3e000000, v5
	v_mul_f32_e32 v5, 0x3fb8aa3b, v41
	v_mul_f32_e32 v35, 0x3fb8aa3b, v35
	v_mul_f32_e32 v15, 0x3fb8aa3b, v15
	v_mul_f32_e32 v27, 0x3fb8aa3b, v27
	v_exp_f32_e32 v5, v5
	v_exp_f32_e32 v35, v35
	v_exp_f32_e32 v15, v15
	v_exp_f32_e32 v40, v27
	v_mul_f32_e32 v7, v7, v38
	v_mul_f32_e32 v37, v4, v37
	v_mul_f32_e32 v38, v4, v5
	v_mul_f32_e32 v35, v4, v35
	v_mul_f32_e32 v27, v15, v50
	v_mul_f32_e32 v15, v4, v40
	v_sub_f32_e32 v4, v43, v41
	v_mul_f32_e32 v4, 0x3fb8aa3b, v4
	v_exp_f32_e32 v49, v4
	v_add_u32_e32 v4, 0x4110, v20
	ds_read2_b32 v[4:5], v4 offset1:1
	v_add_u32_e32 v40, 0x608c, v18
	v_mul_f32_e32 v41, 0x3fb8aa3b, v24
	v_exp_f32_e32 v53, v41
	v_add_u32_e32 v20, 0x4118, v20
	v_add_u32_e32 v18, 0x6094, v18
	ds_read2_b32 v[40:41], v40 offset1:1
	ds_read2_b32 v[42:43], v20 offset1:1
	ds_read2_b32 v[44:45], v18 offset1:1
	s_waitcnt lgkmcnt(3)
	v_mul_f32_e32 v18, 0x3fb8aa3b, v4
	v_mul_f32_e32 v20, v49, v50
	v_sub_f32_e32 v50, v24, v0
	v_sub_f32_e32 v0, v0, v24
	s_waitcnt lgkmcnt(2)
	v_sub_f32_e32 v24, v4, v40
	v_sub_f32_e32 v4, v40, v4
	v_mul_f32_e32 v50, 0x3fb8aa3b, v50
	v_mul_f32_e32 v0, 0x3fb8aa3b, v0
	v_mul_f32_e32 v4, 0x3fb8aa3b, v4
	v_exp_f32_e32 v50, v50
	v_exp_f32_e32 v0, v0
	v_mul_f32_e32 v24, 0x3fb8aa3b, v24
	v_exp_f32_e32 v4, v4
	v_exp_f32_e32 v18, v18
	v_exp_f32_e32 v24, v24
	v_mul_f32_e32 v46, 0x3e000000, v46
	v_mul_f32_e32 v40, v46, v50
	v_mul_f32_e32 v50, v0, v51
	v_mul_f32_e32 v4, v4, v51
	v_sub_f32_e32 v51, v25, v1
	v_sub_f32_e32 v1, v1, v25
	v_mul_f32_e32 v49, v46, v53
	v_mul_f32_e32 v18, v46, v18
	v_mul_f32_e32 v24, v46, v24
	v_mul_f32_e32 v0, 0x3e000000, v47
	v_mul_f32_e32 v46, 0x3fb8aa3b, v25
	v_mul_f32_e32 v47, 0x3fb8aa3b, v5
	v_mul_f32_e32 v51, 0x3fb8aa3b, v51
	v_mul_f32_e32 v1, 0x3fb8aa3b, v1
	v_exp_f32_e32 v46, v46
	v_exp_f32_e32 v47, v47
	v_exp_f32_e32 v51, v51
	v_exp_f32_e32 v1, v1
	v_mul_f32_e32 v25, v0, v46
	v_mul_f32_e32 v46, v0, v47
	v_mul_f32_e32 v47, v0, v51
	v_mul_f32_e32 v51, v1, v52
	v_sub_f32_e32 v1, v5, v41
	v_mul_f32_e32 v1, 0x3fb8aa3b, v1
	v_exp_f32_e32 v1, v1
	v_sub_f32_e32 v5, v41, v5
	v_mul_f32_e32 v41, 0x3fb8aa3b, v22
	v_mul_f32_e32 v5, 0x3fb8aa3b, v5
	v_mul_f32_e32 v53, v0, v1
	v_mul_f32_e32 v0, 0x3e000000, v48
	v_sub_f32_e32 v48, v22, v2
	v_sub_f32_e32 v2, v2, v22
	s_waitcnt lgkmcnt(0)
	v_sub_f32_e32 v22, v42, v44
	v_mul_f32_e32 v1, 0x3fb8aa3b, v42
	v_mul_f32_e32 v48, 0x3fb8aa3b, v48
	v_mul_f32_e32 v22, 0x3fb8aa3b, v22
	v_exp_f32_e32 v5, v5
	v_exp_f32_e32 v41, v41
	v_exp_f32_e32 v1, v1
	v_exp_f32_e32 v48, v48
	v_exp_f32_e32 v22, v22
	v_mul_f32_e32 v2, 0x3fb8aa3b, v2
	v_exp_f32_e32 v2, v2
	v_mul_f32_e32 v5, v5, v52
	v_mul_f32_e32 v41, v0, v41
	v_mul_f32_e32 v52, v0, v1
	v_mul_f32_e32 v48, v0, v48
	v_mul_f32_e32 v22, v0, v22
	v_sub_f32_e32 v0, v44, v42
	v_mul_f32_e32 v0, 0x3fb8aa3b, v0
	v_mul_f32_e32 v54, v2, v39
	v_exp_f32_e32 v0, v0
	v_mul_f32_e32 v1, 0x3fb8aa3b, v23
	v_mul_f32_e32 v2, 0x3fb8aa3b, v43
	v_exp_f32_e32 v1, v1
	v_exp_f32_e32 v2, v2
	v_mul_f32_e32 v39, v0, v39
	v_mul_f32_e32 v0, 0x3e000000, v36
	v_mul_f32_e32 v36, v0, v1
	v_mul_f32_e32 v42, v0, v2
	v_sub_f32_e32 v1, v23, v3
	v_sub_f32_e32 v2, v3, v23
	v_sub_f32_e32 v3, v43, v45
	v_mul_f32_e32 v1, 0x3fb8aa3b, v1
	v_mul_f32_e32 v2, 0x3fb8aa3b, v2
	v_mul_f32_e32 v3, 0x3fb8aa3b, v3
	v_exp_f32_e32 v1, v1
	v_exp_f32_e32 v2, v2
	v_exp_f32_e32 v3, v3
	v_sub_f32_e32 v23, v45, v43
	v_mul_f32_e32 v43, v0, v1
	v_mul_f32_e32 v44, v2, v28
	v_mul_f32_e32 v45, v0, v3
	v_cvt_pk_bf16_f32 v0, v29, v31
	v_cvt_pk_bf16_f32 v1, v34, v37
	v_cvt_pk_bf16_f32 v2, v49, v25
	v_mul_lo_u32 v25, v170, s53
	v_add3_u32 v25, 0, v25, v176
	v_cvt_pk_bf16_f32 v3, v41, v36
	ds_write_b128 v25, v[0:3] offset:54272
	v_cvt_pk_bf16_f32 v0, v13, v17
	v_cvt_pk_bf16_f32 v1, v33, v38
	v_cvt_pk_bf16_f32 v2, v18, v46
	v_mul_lo_u32 v13, v170, s55
	v_cvt_pk_bf16_f32 v3, v52, v42
	ds_write_b128 v25, v[0:3] offset:54400
	v_cvt_pk_bf16_f32 v0, v11, v21
	v_cvt_pk_bf16_f32 v1, v32, v35
	v_cvt_pk_bf16_f32 v2, v40, v47
	v_add3_u32 v11, s54, v13, v176
	v_cvt_pk_bf16_f32 v3, v48, v43
	ds_write_b128 v11, v[0:3]
	v_cvt_pk_bf16_f32 v0, v8, v12
	v_cvt_pk_bf16_f32 v1, v30, v27
	v_cvt_pk_bf16_f32 v2, v50, v51
	v_add3_u32 v8, s56, v13, v176
	v_mul_f32_e32 v23, 0x3fb8aa3b, v23
	v_cvt_pk_bf16_f32 v3, v54, v44
	ds_write_b128 v8, v[0:3]
	v_cvt_pk_bf16_f32 v0, v7, v10
	v_cvt_pk_bf16_f32 v1, v26, v15
	v_cvt_pk_bf16_f32 v2, v24, v53
	v_add3_u32 v7, s57, v13, v176
	v_exp_f32_e32 v23, v23
	v_cvt_pk_bf16_f32 v3, v22, v45
	ds_write_b128 v7, v[0:3]
	v_cvt_pk_bf16_f32 v0, v6, v9
	v_cvt_pk_bf16_f32 v1, v14, v20
	v_cvt_pk_bf16_f32 v2, v4, v5
	v_lshl_add_u64 v[4:5], v[118:119], 0, s[8:9]
	v_mov_b32_e32 v17, v177
	v_lshl_add_u64 v[8:9], v[4:5], 0, v[16:17]
	v_add_co_u32_e32 v4, vcc, s34, v8
	v_mul_f32_e32 v23, v23, v28
	s_nop 0
	v_addc_co_u32_e32 v5, vcc, 0, v9, vcc
	v_cvt_pk_bf16_f32 v3, v39, v23
	s_waitcnt vmcnt(0)
	v_mov_b32_e32 v4, v224
	v_mov_b32_e32 v5, v225
	v_mov_b32_e32 v6, v226
	v_mov_b32_e32 v7, v227
	v_lshl_add_u64 v[8:9], v[8:9], 0, s[2:3]
	v_mov_b32_e32 v8, v228
	v_mov_b32_e32 v9, v229
	v_mov_b32_e32 v10, v230
	v_mov_b32_e32 v11, v231
	v_add3_u32 v12, s58, v13, v176
	ds_write_b128 v12, v[0:3]
	v_lshlrev_b32_e32 v16, 1, v170
	v_mul_u32_u24_e32 v17, 0x900, v19
	v_add3_u32 v16, s59, v16, v17
	s_cselect_b64 s[2:3], -1, 0
	s_addk_i32 s0, 0xf000
	s_lshr_b32 s0, s0, 11
	s_ashr_i32 s1, s12, 5
	s_cmp_gt_i32 s61, 63
	s_cselect_b64 s[18:19], -1, 0
	s_and_b64 vcc, s[18:19], exec
	s_cselect_b32 s13, s0, s1
	s_lshl_b32 s7, s13, 2
	s_or_b32 s16, s7, 2
	s_lshl_b64 s[0:1], s[16:17], 18
	s_add_u32 s0, s25, s0
	s_addc_u32 s1, s26, s1
	s_or_b32 s14, s7, 3
	s_waitcnt vmcnt(1)
	v_lshlrev_b32_e32 v0, 16, v4
	v_cvt_pk_bf16_f32 v0, v0, v177
	v_and_b32_e32 v1, 0xffff0000, v4
	ds_write_b16 v16, v0
	v_cvt_pk_bf16_f32 v0, v1, v177
	v_lshlrev_b32_e32 v2, 16, v5
	ds_write_b16 v16, v0 offset:144
	v_cvt_pk_bf16_f32 v0, v2, v177
	v_and_b32_e32 v3, 0xffff0000, v5
	ds_write_b16 v16, v0 offset:288
	v_cvt_pk_bf16_f32 v0, v3, v177
	v_lshlrev_b32_e32 v4, 16, v6
	ds_write_b16 v16, v0 offset:432
	v_cvt_pk_bf16_f32 v0, v4, v177
	v_and_b32_e32 v5, 0xffff0000, v6
	ds_write_b16 v16, v0 offset:576
	v_cvt_pk_bf16_f32 v0, v5, v177
	v_lshlrev_b32_e32 v6, 16, v7
	ds_write_b16 v16, v0 offset:720
	v_cvt_pk_bf16_f32 v0, v6, v177
	v_and_b32_e32 v7, 0xffff0000, v7
	ds_write_b16 v16, v0 offset:864
	v_cvt_pk_bf16_f32 v0, v7, v177
	s_waitcnt vmcnt(0)
	v_lshlrev_b32_e32 v12, 16, v8
	ds_write_b16 v16, v0 offset:1008
	v_cvt_pk_bf16_f32 v0, v12, v177
	v_and_b32_e32 v8, 0xffff0000, v8
	ds_write_b16 v16, v0 offset:1152
	v_cvt_pk_bf16_f32 v0, v8, v177
	v_lshlrev_b32_e32 v13, 16, v9
	ds_write_b16 v16, v0 offset:1296
	v_cvt_pk_bf16_f32 v0, v13, v177
	v_and_b32_e32 v9, 0xffff0000, v9
	ds_write_b16 v16, v0 offset:1440
	v_cvt_pk_bf16_f32 v0, v9, v177
	v_lshlrev_b32_e32 v14, 16, v10
	ds_write_b16 v16, v0 offset:1584
	v_cvt_pk_bf16_f32 v0, v14, v177
	v_and_b32_e32 v10, 0xffff0000, v10
	ds_write_b16 v16, v0 offset:1728
	v_cvt_pk_bf16_f32 v0, v10, v177
	v_lshlrev_b32_e32 v15, 16, v11
	ds_write_b16 v16, v0 offset:1872
	v_cvt_pk_bf16_f32 v0, v15, v177
	v_and_b32_e32 v11, 0xffff0000, v11
	ds_write_b16 v16, v0 offset:2016
	v_cvt_pk_bf16_f32 v0, v11, v177
	ds_write_b16 v16, v0 offset:2160
	v_lshlrev_b32_e32 v0, 11, v171
	v_and_b32_e32 v2, 0x7800, v0
	v_mov_b32_e32 v3, v177
	v_lshl_add_u64 v[0:1], s[0:1], 0, v[2:3]
	s_lshl_b64 s[0:1], s[14:15], 18
	s_add_u32 s0, s25, s0
	s_addc_u32 s1, s26, s1
	v_lshl_add_u64 v[2:3], s[0:1], 0, v[2:3]
	s_cbranch_vccz .LBB0_1370
	v_readlane_b32 s68, v254, 16
	v_readlane_b32 s69, v254, 17
	s_sub_i32 s70, s61, 64
	s_lshl_b32 s70, s70, 3
	s_or_b32 s70, s70, s24
	s_mov_b32 s71, 0
	s_lshl_b64 s[70:71], s[70:71], 16
	s_add_u32 s68, s68, s70
	s_addc_u32 s69, s69, s71
	s_add_u32 s70, s68, 0x8000
	s_addc_u32 s71, s69, 0
	v_lshlrev_b32_e32 v186, 4, v171
	global_load_dwordx4 v[132:135], v186, s[68:69]
	global_load_dwordx4 v[128:131], v186, s[70:71]
	v_add_u32_e32 v187, 0x2000, v186
	global_load_dwordx4 v[140:143], v187, s[68:69]
	global_load_dwordx4 v[136:139], v187, s[70:71]
	v_add_u32_e32 v187, 0x4000, v186
	global_load_dwordx4 v[148:151], v187, s[68:69]
	global_load_dwordx4 v[144:147], v187, s[70:71]
	v_add_u32_e32 v187, 0x6000, v186
	global_load_dwordx4 v[156:159], v187, s[68:69]
	global_load_dwordx4 v[152:155], v187, s[70:71]
	v_ashrrev_i32_e32 v117, 31, v116
	s_branch .LBB0_1354
	v_ashrrev_i32_e32 v4, 4, v171
	v_ashrrev_i32_e32 v5, 31, v4
	v_lshlrev_b64 v[4:5], 2, v[4:5]
	v_lshl_add_u64 v[6:7], v[0:1], 0, v[4:5]
	v_lshl_add_u64 v[4:5], v[2:3], 0, v[4:5]
	global_load_dword v132, v[6:7], off
	global_load_dword v133, v[6:7], off offset:512
	global_load_dword v134, v[6:7], off offset:1024
	global_load_dword v135, v[6:7], off offset:1536
	global_load_dword v128, v[4:5], off
	global_load_dword v129, v[4:5], off offset:512
	global_load_dword v130, v[4:5], off offset:1024
	global_load_dword v131, v[4:5], off offset:1536
	v_cndmask_b32_e64 v4, 0, 1, s[18:19]
	v_cmp_ne_u32_e64 s[0:1], 1, v4
	s_andn2_b64 vcc, exec, s[18:19]
	s_cbranch_vccz .LBB0_1371
